# w4 + attention unit tail (last PV block): all 16 V-fragment ds_reads issued ahead into dead key-loop VGPRs, counted lgkmcnt waits (MFMA/LDS interleave)
# baseline (speedup 1.0000x reference)
.LBB0_1333:
	s_waitcnt lgkmcnt(0)
	v_lshl_add_u32 v0, s72, 14, v124
	ds_read_b128 v[80:83], v0 offset:53248
	ds_read_b128 v[96:99], v0 offset:55296
	ds_read_b128 v[180:183], v0 offset:61440
	ds_read_b128 v[188:191], v0 offset:63488
	ds_read_b128 v[64:67], v0 offset:49152
	ds_read_b128 v[72:75], v0 offset:51200
	ds_read_b128 v[140:143], v0 offset:57344
	ds_read_b128 v[148:151], v0 offset:59392
	s_mov_b32 s49, s48
	s_mov_b32 s50, s48
	s_mov_b32 s51, s48
	s_and_b64 s[98:99], s[20:21], s[26:27]
	s_and_b64 s[98:99], s[98:99], s[6:7]
	s_and_saveexec_b64 s[94:95], s[98:99]
	s_cbranch_execz .Lpf_end
	s_getreg_b32 s32, hwreg(HW_REG_XCC_ID, 0, 4)
	s_and_b32 s32, s32, 7
	s_lshl_b32 s98, s32, 10
	s_add_i32 s98, s98, 0x2000
	v_mov_b32_e32 v221, s98
	v_mov_b32_e32 v220, 1
	global_atomic_add v220, v221, v220, s[16:17] sc0
	s_mov_b32 s80, 1
.Lpf_end:
	s_or_b64 exec, exec, s[94:95]
	s_cmp_lg_u64 s[28:29], 0
	ds_read_b128 v[68:71], v0 offset:50176
	ds_read_b128 v[76:79], v0 offset:52224
	ds_read_b128 v[84:87], v0 offset:54272
	ds_read_b128 v[100:103], v0 offset:56320
	global_load_dwordx2 v[176:177], v1, s[18:19]
	global_load_dwordx4 v[160:163], v[110:111], off
	global_load_dwordx4 v[164:167], v[110:111], off offset:64
	global_load_dwordx4 v[168:171], v[110:111], off offset:128
	global_load_dwordx4 v[172:175], v[110:111], off offset:192
	global_load_dwordx4 v[204:207], v[110:111], off offset:256
	global_load_dwordx4 v[208:211], v[110:111], off offset:320
	global_load_dwordx4 v[212:215], v[110:111], off offset:384
	global_load_dwordx4 v[216:219], v[110:111], off offset:448
	s_waitcnt lgkmcnt(11)
	v_mfma_f32_16x16x32_bf16 v[22:25], v[80:83], v[14:17], v[42:45]
	ds_read_b128 v[144:147], v0 offset:58368
	s_waitcnt lgkmcnt(11)
	v_mfma_f32_16x16x32_bf16 v[26:29], v[96:99], v[14:17], v[34:37]
	ds_read_b128 v[152:155], v0 offset:60416
	s_waitcnt lgkmcnt(11)
	v_mfma_f32_16x16x32_bf16 v[42:45], v[180:183], v[14:17], v[46:49]
	ds_read_b128 v[184:187], v0 offset:62464
	s_waitcnt lgkmcnt(11)
	v_mfma_f32_16x16x32_bf16 v[46:49], v[188:191], v[14:17], v[38:41]
	ds_read_b128 v[192:195], v0 offset:64512
	s_waitcnt lgkmcnt(11)
	v_mfma_f32_16x16x32_bf16 v[10:13], v[64:67], v[14:17], v[30:33]
	s_waitcnt lgkmcnt(10)
	v_mfma_f32_16x16x32_bf16 v[18:21], v[72:75], v[14:17], v[50:53]
	s_waitcnt lgkmcnt(9)
	v_mfma_f32_16x16x32_bf16 v[30:33], v[140:143], v[14:17], v[58:61]
	s_waitcnt lgkmcnt(8)
	v_mfma_f32_16x16x32_bf16 v[34:37], v[148:151], v[14:17], v[54:57]
	s_waitcnt lgkmcnt(7)
	v_mfma_f32_16x16x32_bf16 v[10:13], v[68:71], v[6:9], v[10:13]
	s_waitcnt lgkmcnt(6)
	v_mfma_f32_16x16x32_bf16 v[18:21], v[76:79], v[6:9], v[18:21]
	s_waitcnt lgkmcnt(5)
	v_mfma_f32_16x16x32_bf16 v[22:25], v[84:87], v[6:9], v[22:25]
	s_waitcnt lgkmcnt(4)
	v_mfma_f32_16x16x32_bf16 v[26:29], v[100:103], v[6:9], v[26:29]
	s_waitcnt lgkmcnt(3)
	v_mfma_f32_16x16x32_bf16 v[30:33], v[144:147], v[6:9], v[30:33]
	s_waitcnt lgkmcnt(2)
	v_mfma_f32_16x16x32_bf16 v[34:37], v[152:155], v[6:9], v[34:37]
	s_waitcnt lgkmcnt(1)
	v_mfma_f32_16x16x32_bf16 v[38:41], v[184:187], v[6:9], v[42:45]
	s_waitcnt lgkmcnt(0)
	v_mfma_f32_16x16x32_bf16 v[42:45], v[192:195], v[6:9], v[46:49]
	s_nop 2
	v_mov_b64_e32 v[46:47], s[48:49]
	v_mov_b64_e32 v[48:49], s[50:51]
	s_nop 1
	v_mfma_f32_16x16x32_bf16 v[2:5], v[46:49], v[14:17], v[2:5]
	v_mfma_f32_16x16x32_bf16 v[2:5], v[46:49], v[6:9], v[2:5]
	s_cbranch_scc0 .LBB0_1337
	s_nop 6
	v_or_b32_e32 v4, s30, v129
	v_ashrrev_i32_e32 v5, 31, v4
	v_lshlrev_b64 v[4:5], 9, v[4:5]
	v_lshl_add_u64 v[4:5], s[28:29], 0, v[4:5]
	v_lshlrev_b32_e32 v0, 2, v106
	v_lshl_add_u64 v[4:5], v[4:5], 0, v[0:1]
	global_store_dwordx4 v[4:5], v[10:13], off
	global_store_dwordx4 v[4:5], v[18:21], off offset:64
	global_store_dwordx4 v[4:5], v[22:25], off offset:128
	global_store_dwordx4 v[4:5], v[26:29], off offset:192
	global_store_dwordx4 v[4:5], v[30:33], off offset:256
	global_store_dwordx4 v[4:5], v[34:37], off offset:320
	global_store_dwordx4 v[4:5], v[38:41], off offset:384
	global_store_dwordx4 v[4:5], v[42:45], off offset:448
	s_and_saveexec_b64 s[34:35], s[8:9]
	v_readlane_b32 s72, v255, 9
	v_readlane_b32 s73, v255, 10
	s_cbranch_execz .LBB0_1336
	s_add_i32 s0, s30, s70
	s_add_i32 s30, s0, 0x4000
	v_or_b32_e32 v4, s30, v109
	v_ashrrev_i32_e32 v5, 31, v4
	v_lshl_add_u64 v[4:5], v[4:5], 2, s[28:29]
	s_addk_i32 s0, 0x4080
	global_store_dword v[4:5], v113, off
	v_or_b32_e32 v4, s0, v109
	v_ashrrev_i32_e32 v5, 31, v4
	v_lshl_add_u64 v[4:5], v[4:5], 2, s[28:29]
	global_store_dword v[4:5], v2, off
